# v062 + FFN-in phase start: row-scale staging deferred behind the first LDS-DMA loads (prologue de-serialisation)
# speedup vs baseline: 1.0216x; 1.0012x over previous
.LBB0_651:
	s_cmp_gt_i32 s9, -1
	v_readlane_b32 s12, v255, 6
	s_cselect_b64 s[10:11], -1, 0
	v_readlane_b32 s13, v255, 7
	s_and_b64 s[10:11], s[10:11], s[12:13]
	s_and_saveexec_b64 s[12:13], s[10:11]
	s_cbranch_execz .LBB0_653
	v_lshl_or_b32 v2, s9, 8, v0
	v_lshl_add_u64 v[204:205], v[2:3], 4, s[16:17]
	v_add_co_u32_e32 v204, vcc, 0x100000, v204
	s_nop 1
	v_addc_co_u32_e32 v205, vcc, 0, v205, vcc
	global_load_dwordx4 v[200:203], v[204:205], off

.LBB0_658:
	s_add_u32 s57, s16, 0x5400000
	v_and_b32_e32 v18, 15, v17
	v_lshrrev_b32_e32 v17, 1, v17
	s_addc_u32 s74, s17, 0
	v_and_b32_e32 v17, 24, v17
	s_add_u32 s16, s16, 0x100000
	v_lshlrev_b32_e32 v19, 1, v17
	s_addc_u32 s17, s17, 0
	v_lshl_or_b32 v141, s10, 6, v18
	v_lshl_or_b32 v19, v18, 6, v19
	v_lshlrev_b32_e32 v18, 2, v18
	s_lshl_b32 s11, s11, 5
	s_lshl_b32 s12, s10, 13
	v_and_b32_e32 v20, 32, v18
	s_and_b32 s75, s11, 0x60
	s_add_i32 m0, s35, 0x18000
	v_lshl_add_u64 v[10:11], v[10:11], 0, s[30:31]
	v_bitop3_b32 v21, v19, s12, v20 bitop3:0xde
	s_lshl_b32 s12, s75, 7
	s_waitcnt vmcnt(2)
	s_barrier
	v_readlane_b32 s64, v255, 6
	v_readlane_b32 s65, v255, 7
	s_nop 3
	s_and_saveexec_b64 s[72:73], s[64:65]
	v_mov_b32_e32 v206, v201
	v_mov_b32_e32 v207, v202
	v_mov_b32_e32 v201, v203
	v_pk_add_f32 v[200:201], v[206:207], v[200:201]
	s_nop 0
	v_add_f32_e32 v200, v200, v201
	v_fmamk_f32 v200, v200, 0x3a800000, v193
	v_rsq_f32_e32 v200, v200
	s_nop 0
	ds_write_b32 v194, v200
	s_or_b64 exec, exec, s[72:73]
	global_load_lds_dwordx4 v[10:11], off
	v_lshl_add_u64 v[8:9], v[8:9], 0, s[30:31]
	s_add_i32 m0, s35, 0x1a000
	s_add_i32 s76, s35, 0x8000
	s_add_i32 s77, s35, 0xa000
	v_bitop3_b32 v148, v19, s12, v20 bitop3:0xde
	global_load_lds_dwordx4 v[8:9], off
	v_lshl_add_u64 v[4:5], v[4:5], 0, s[30:31]
	s_mov_b32 m0, s76
	s_add_u32 s12, s70, 0x40080
	global_load_lds_dwordx4 v[4:5], off
	v_lshl_add_u64 v[4:5], v[6:7], 0, s[30:31]
	s_mov_b32 m0, s77
	s_addc_u32 s13, s71, 0
	global_load_lds_dwordx4 v[4:5], off
	s_add_i32 m0, s35, 0x1c000
	v_lshl_add_u64 v[4:5], s[12:13], 0, v[134:135]
	global_load_lds_dwordx4 v[4:5], off
	v_lshl_add_u64 v[4:5], s[12:13], 0, v[138:139]
	s_add_i32 m0, s35, 0x1e000
	s_cmpk_lt_u32 s6, 0x100
	global_load_lds_dwordx4 v[4:5], off
	v_lshlrev_b32_e32 v4, 14, v2
	v_and_b32_e32 v4, 0xffff8000, v4
	v_lshl_add_u32 v4, v12, 11, v4
	v_and_b32_e32 v2, 1, v2
	v_lshl_or_b32 v2, v2, 6, v4
	v_lshl_add_u32 v142, v13, 1, v2
	v_lshlrev_b32_e32 v2, 14, v14
	s_cselect_b64 s[18:19], -1, 0
	s_lshl_b32 s6, s10, 8
	v_and_b32_e32 v2, 0xffff8000, v2
	s_waitcnt vmcnt(6)
	s_add_i32 s6, s6, 0
	v_lshl_add_u32 v2, v15, 11, v2
	v_and_b32_e32 v4, 1, v14
	s_add_i32 s10, s6, 0x20000
	s_add_i32 s6, s6, 0x20200
	v_lshl_or_b32 v2, v4, 6, v2
	v_and_or_b32 v140, s11, 32, v17
	s_ashr_i32 s78, s4, 31
	v_add_u32_e32 v149, s10, v18
	v_add_u32_e32 v150, s6, v18
	v_mov_b32_e32 v143, v3
	v_lshl_add_u32 v144, v16, 1, v2
	v_mov_b32_e32 v145, v3
	s_mov_b32 s79, 0
	v_add_u32_e32 v151, 0, v21
	s_barrier
	s_branch .LBB0_661
